# S5 local-state pass: one item per wave on all workgroups (was two per wave on the 128 idle-slot workgroups)
# speedup vs baseline: 1.0019x; 1.0001x over previous
; #define RELAUNDER() do { int t_ = threadIdx.x; asm volatile("" : "+v"(t_)); tid = t_; lane = tid & 63; wave = __builtin_amdgcn_readfirstlane(tid >> 6); } while (0)
; __global__ void __launch_bounds__(NWAVES * 64, 2) hymba_fwd(Args args) {
;     ...
;             if (G == 256 && bx >= 128) {
;                 __syncthreads();
;                 if (wave == 0) { unsigned* sucnt = (unsigned*)(ws + WS_SUCNT) + layer * 64; unsigned spins = 0;
;                     while ((unsigned)__builtin_amdgcn_readfirstlane(__hip_atomic_load(sucnt, __ATOMIC_RELAXED, __HIP_MEMORY_SCOPE_AGENT)) < 512u) { __builtin_amdgcn_s_sleep(4); if (++spins > (1u << 22)) break; }
;                     __builtin_amdgcn_fence(__ATOMIC_ACQUIRE, "agent"); asm volatile("s_waitcnt vmcnt(0)" ::: "memory"); }
;                 __syncthreads();
;                 RELAUNDER();
.LBB0_332:
	v_readlane_b32 s2, v252, 12
	v_readlane_b32 s3, v252, 13
	s_and_b64 vcc, exec, s[2:3]
	s_cbranch_vccnz .LBB0_372
	s_cmp_lg_u32 s22, 0
	s_barrier
	s_cbranch_scc1 .LBB0_343
	s_mov_b32 s8, 0x400001
	s_branch .LBB0_336

; #define LAS __attribute__((address_space(3)))
; template <bool OUT> __device__ __forceinline__ void s5_item(const PA& a, LAS unsigned char* lds, int layer, int item, int wave, int lane) {
;     const int b = item >> 10, g = (item >> 6) & 15, c = item & 63, lg = layer * 16 + g;
;     const bf16* PROJ = (const bf16*)(a.ws + WS_PROJ);
;     const float* sa = (const float*)(a.ws + WS_S5A) + (size_t)lg * 256;
;     float* XL = (float*)(a.ws + WS_XLOC) + (size_t)((b * 16 + g) * 64) * 128;
;     const float ar = sa[lane], ai = sa[64 + lane];
;     float xr = 0.f, xi = 0.f;
;     if (OUT) { xr = XL[c * 128 + lane]; xi = XL[c * 128 + 64 + lane]; }
;     const int l15 = lane & 15, quad = lane >> 4;
;     const bf16x8 zero8 = {0, 0, 0, 0, 0, 0, 0, 0};
;     bf16x8 bfr[8];
; #pragma unroll
;     for (int nt = 0; nt < 8; ++nt) bfr[nt] = (quad < 2) ? *(const bf16x8*)((const bf16*)(a.ws + WS_S5B) + (size_t)lg * 2048 + (nt * 16 + l15) * 16 + quad * 8) : zero8;
;     bf16x8 cfr[4];
;     if (OUT) {
; #pragma unroll
;         for (int ks = 0; ks < 4; ++ks) cfr[ks] = *(const bf16x8*)((const bf16*)(a.ws + WS_S5C) + (size_t)lg * 2048 + l15 * 128 + ks * 32 + quad * 8);
;     }
;     const float dsk = a.in[13][layer * 256 + g * 16 + l15];
;     LAS float* BU = (LAS float*)(lds + wave * 12800);
;     LAS bf16* X = (LAS bf16*)(lds + wave * 12800 + 8448);
;     const size_t rowb = (size_t)b * T + (size_t)c * 128;
;     bf16x8 afr_n = (quad < 2) ? *(const bf16x8*)(PROJ + (rowb + l15) * DIN + 1024 + g * 16 + quad * 8) : zero8;
;     bf16 ue_n[4] = {0, 0, 0, 0}, se_n[4] = {0, 0, 0, 0};
;     if (OUT) {
; #pragma unroll
;         for (int j = 0; j < 4; ++j) { ue_n[j] = PROJ[(rowb + quad * 4 + j) * DIN + 1024 + g * 16 + l15]; se_n[j] = PROJ[(rowb + quad * 4 + j) * DIN + 1280 + g * 16 + l15]; }
;     }
;     f32x4 accn[8];
; #pragma unroll
;     for (int nt = 0; nt < 8; ++nt) accn[nt] = __builtin_amdgcn_mfma_f32_16x16x32_bf16(afr_n, bfr[nt], (f32x4){0.f, 0.f, 0.f, 0.f}, 0, 0, 0);
; #pragma unroll
;     for (int nt = 0; nt < 8; ++nt)
; #pragma unroll
;         for (int j = 0; j < 4; ++j) BU[(quad * 4 + j) * 132 + nt * 16 + l15] = accn[nt][j];
;     afr_n = (quad < 2) ? *(const bf16x8*)(PROJ + (rowb + 16 + l15) * DIN + 1024 + g * 16 + quad * 8) : zero8;
;     for (int blk = 0; blk < 8; ++blk) {
;         const size_t row0 = rowb + blk * 16;
;         bf16 ue[4], se[4];
; #pragma unroll
.LBB0_343:
	v_mov_b32_e32 v0, v234
	s_barrier
	v_readlane_b32 s3, v252, 16
	v_readfirstlane_b32 s2, v0
	s_ashr_i32 s2, s2, 6
	s_add_i32 s8, s3, s2
	s_cmpk_gt_i32 s8, 0x7ff
	s_cbranch_scc1 .LBB0_372
	v_and_b32_e32 v207, 63, v0
	v_and_b32_e32 v196, 31, v0
	v_bfe_u32 v197, v0, 5, 1
	v_lshlrev_b32_e32 v204, 2, v196
	v_mul_u32_u24_e32 v205, 0x1c00, v196
	v_lshl_add_u32 v205, v197, 4, v205
	v_lshlrev_b32_e32 v206, 5, v196
	v_lshl_add_u32 v206, v197, 4, v206
	v_readlane_b32 s3, v254, 44
	s_lshl_b32 s9, s3, 4
	s_bfe_u32 s11, s8, 0x40006
	s_or_b32 s62, s11, s9
	s_lshl_b64 s[2:3], s[62:63], 10
	s_add_u32 s2, s2, s68
	s_addc_u32 s3, s3, s69
	s_add_u32 s2, s2, 0x1500000
	s_addc_u32 s3, s3, 0
	global_load_dword v176, v204, s[2:3]
	global_load_dword v184, v204, s[2:3] offset:128
	global_load_dword v177, v204, s[2:3] offset:256
	global_load_dword v185, v204, s[2:3] offset:384
	s_lshl_b64 s[4:5], s[62:63], 12
	s_add_u32 s4, s4, s68
	s_addc_u32 s5, s5, s69
	s_add_u32 s4, s4, 0x1510000
	s_addc_u32 s5, s5, 0
	global_load_dwordx4 v[128:131], v206, s[4:5]
	global_load_dwordx4 v[132:135], v206, s[4:5] offset:1024
	global_load_dwordx4 v[136:139], v206, s[4:5] offset:2048
	global_load_dwordx4 v[140:143], v206, s[4:5] offset:3072
	s_ashr_i32 s10, s8, 10
	s_and_b32 s14, s8, 63
	s_mul_i32 s12, s10, 0x3800000
	s_mul_i32 s14, s14, 0xe0000
	s_add_u32 s12, s12, s14
	s_lshl_b32 s14, s11, 5
	s_add_u32 s12, s12, s14
	s_add_u32 s12, s12, 0x800
	s_add_u32 s12, s12, s60
	s_addc_u32 s13, s61, 0
	global_load_dwordx4 v[144:147], v205, s[12:13]
	s_add_u32 s12, s12, 0x38000
	s_addc_u32 s13, s13, 0
	global_load_dwordx4 v[148:151], v205, s[12:13]
	s_add_u32 s12, s12, 0x38000
	s_addc_u32 s13, s13, 0
	global_load_dwordx4 v[152:155], v205, s[12:13]
	s_add_u32 s12, s12, 0x38000
	s_addc_u32 s13, s13, 0
	global_load_dwordx4 v[156:159], v205, s[12:13]
	s_waitcnt vmcnt(8)
	v_cmp_gt_u32_e32 vcc, 32, v207
	v_mul_f32_e32 v200, v177, v177
	v_mul_f32_e32 v201, v176, v177
	v_fma_f32 v196, v176, v176, -v200
	v_add_f32_e32 v197, v201, v201
	v_mul_f32_e32 v200, v197, v197
	v_mul_f32_e32 v201, v196, v197
	v_fma_f32 v198, v196, v196, -v200
	v_add_f32_e32 v199, v201, v201
	v_cndmask_b32_e32 v180, 1.0, v198, vcc
	v_cndmask_b32_e32 v181, 0, v199, vcc
	v_mul_f32_e32 v200, v199, v199
	v_mul_f32_e32 v201, v198, v199
	v_fma_f32 v178, v198, v198, -v200
	v_add_f32_e32 v179, v201, v201
	v_mul_f32_e32 v200, v179, v179
	v_mul_f32_e32 v201, v178, v179
	v_fma_f32 v196, v178, v178, -v200
	v_add_f32_e32 v197, v201, v201
	v_mul_f32_e32 v200, v197, v197
	v_mul_f32_e32 v201, v196, v197
	v_fma_f32 v182, v196, v196, -v200
	v_add_f32_e32 v183, v201, v201
	v_mul_f32_e32 v200, v185, v185
	v_mul_f32_e32 v201, v184, v185
	v_fma_f32 v196, v184, v184, -v200
	v_add_f32_e32 v197, v201, v201
	v_mul_f32_e32 v200, v197, v197
	v_mul_f32_e32 v201, v196, v197
	v_fma_f32 v198, v196, v196, -v200
	v_add_f32_e32 v199, v201, v201
	v_cndmask_b32_e32 v188, 1.0, v198, vcc
	v_cndmask_b32_e32 v189, 0, v199, vcc
	v_mul_f32_e32 v200, v199, v199
	v_mul_f32_e32 v201, v198, v199
	v_fma_f32 v186, v198, v198, -v200
	v_add_f32_e32 v187, v201, v201
	v_mul_f32_e32 v200, v187, v187
	v_mul_f32_e32 v201, v186, v187
	v_fma_f32 v196, v186, v186, -v200
	v_add_f32_e32 v197, v201, v201
	v_mul_f32_e32 v200, v197, v197
	v_mul_f32_e32 v201, v196, v197
	v_fma_f32 v190, v196, v196, -v200
	v_add_f32_e32 v191, v201, v201
	s_waitcnt vmcnt(3)
	v_mfma_f32_32x32x16_bf16 v[0:15], v[144:147], v[128:131], 0
	v_mfma_f32_32x32x16_bf16 v[16:31], v[144:147], v[132:135], 0
	v_mfma_f32_32x32x16_bf16 v[32:47], v[144:147], v[136:139], 0
	v_mfma_f32_32x32x16_bf16 v[48:63], v[144:147], v[140:143], 0
	s_waitcnt vmcnt(2)
	v_mfma_f32_32x32x16_bf16 v[64:79], v[148:151], v[128:131], 0
	v_mfma_f32_32x32x16_bf16 v[80:95], v[148:151], v[132:135], 0
	v_mfma_f32_32x32x16_bf16 v[96:111], v[148:151], v[136:139], 0
	v_mfma_f32_32x32x16_bf16 v[112:127], v[148:151], v[140:143], 0
	s_nop 7
	s_nop 7
	v_fma_f32 v1, v176, v0, v1
	v_fma_f32 v33, v176, v32, v33
	v_fma_f32 v1, -v177, v32, v1
	v_fma_f32 v33, v177, v0, v33
	v_fma_f32 v5, v176, v4, v5
	v_fma_f32 v37, v176, v36, v37
	v_fma_f32 v5, -v177, v36, v5
	v_fma_f32 v37, v177, v4, v37
	v_fma_f32 v9, v176, v8, v9
	v_fma_f32 v41, v176, v40, v41
	v_fma_f32 v9, -v177, v40, v9
	v_fma_f32 v41, v177, v8, v41
	v_fma_f32 v13, v176, v12, v13
	v_fma_f32 v45, v176, v44, v45
	v_fma_f32 v13, -v177, v44, v13
	v_fma_f32 v45, v177, v12, v45
	v_fma_f32 v2, v176, v1, v2
	v_fma_f32 v34, v176, v33, v34
	v_fma_f32 v2, -v177, v33, v2
	v_fma_f32 v34, v177, v1, v34
	v_fma_f32 v6, v176, v5, v6
	v_fma_f32 v38, v176, v37, v38
	v_fma_f32 v6, -v177, v37, v6
	v_fma_f32 v38, v177, v5, v38
	v_fma_f32 v10, v176, v9, v10
	v_fma_f32 v42, v176, v41, v42
	v_fma_f32 v10, -v177, v41, v10
	v_fma_f32 v42, v177, v9, v42
	v_fma_f32 v14, v176, v13, v14
	v_fma_f32 v46, v176, v45, v46
	v_fma_f32 v14, -v177, v45, v14
	v_fma_f32 v46, v177, v13, v46
	v_fma_f32 v3, v176, v2, v3
	v_fma_f32 v35, v176, v34, v35
	v_fma_f32 v3, -v177, v34, v3
	v_fma_f32 v35, v177, v2, v35
	v_fma_f32 v7, v176, v6, v7
	v_fma_f32 v39, v176, v38, v39
	v_fma_f32 v7, -v177, v38, v7
	v_fma_f32 v39, v177, v6, v39
	v_fma_f32 v11, v176, v10, v11
	v_fma_f32 v43, v176, v42, v43
	v_fma_f32 v11, -v177, v42, v11
	v_fma_f32 v43, v177, v10, v43
	v_fma_f32 v15, v176, v14, v15
	v_fma_f32 v47, v176, v46, v47
	v_fma_f32 v15, -v177, v46, v15
	v_fma_f32 v47, v177, v14, v47
	v_fma_f32 v7, v178, v3, v7
	v_fma_f32 v39, v178, v35, v39
	v_fma_f32 v7, -v179, v35, v7
	v_fma_f32 v39, v179, v3, v39
	v_fma_f32 v11, v178, v7, v11
	v_fma_f32 v43, v178, v39, v43
	v_fma_f32 v11, -v179, v39, v11
	v_fma_f32 v43, v179, v7, v43
	v_fma_f32 v15, v178, v11, v15
; __device__ __forceinline__ unsigned f2bf(float f) { unsigned u = __builtin_bit_cast(unsigned, f); return (u + 0x7fffu + ((u >> 16) & 1u)) >> 16; }
; template <bool OUT> __device__ __forceinline__ void s5_item(const PA& a, LAS unsigned char* lds, int layer, int item, int wave, int lane) {
;     ...
;     for (int nt = 0; nt < 8; ++nt) accn[nt] = __builtin_amdgcn_mfma_f32_16x16x32_bf16(afr_n, bfr[nt], (f32x4){0.f, 0.f, 0.f, 0.f}, 0, 0, 0);
; #pragma unroll
;     for (int nt = 0; nt < 8; ++nt)
; #pragma unroll
;         for (int j = 0; j < 4; ++j) BU[(quad * 4 + j) * 132 + nt * 16 + l15] = accn[nt][j];
;     afr_n = (quad < 2) ? *(const bf16x8*)(PROJ + (rowb + 16 + l15) * DIN + 1024 + g * 16 + quad * 8) : zero8;
;     for (int blk = 0; blk < 8; ++blk) {
;         const size_t row0 = rowb + blk * 16;
;         bf16 ue[4], se[4];
; #pragma unroll
;         for (int j = 0; j < 4; ++j) { ue[j] = ue_n[j]; se[j] = se_n[j]; }
;         if (blk + 1 < 8) {
; #pragma unroll
;             for (int nt = 0; nt < 8; ++nt) accn[nt] = __builtin_amdgcn_mfma_f32_16x16x32_bf16(afr_n, bfr[nt], (f32x4){0.f, 0.f, 0.f, 0.f}, 0, 0, 0);
;             if (blk + 2 < 8) afr_n = (quad < 2) ? *(const bf16x8*)(PROJ + (row0 + 32 + l15) * DIN + 1024 + g * 16 + quad * 8) : zero8;
;             if (OUT) {
; #pragma unroll
;                 for (int j = 0; j < 4; ++j) { ue_n[j] = PROJ[(row0 + 16 + quad * 4 + j) * DIN + 1024 + g * 16 + l15]; se_n[j] = PROJ[(row0 + 16 + quad * 4 + j) * DIN + 1280 + g * 16 + l15]; }
;             }
;         }
; #pragma unroll
;         for (int t = 0; t < 16; ++t) {
;             const float br = BU[t * 132 + lane], bi = BU[t * 132 + 64 + lane];
;             const float nr = ar * xr - ai * xi + br, ni = ar * xi + ai * xr + bi; xr = nr; xi = ni;
;             if (OUT) { X[t * 136 + lane] = (bf16)f2bf(xr); X[t * 136 + 64 + lane] = (bf16)f2bf(xi); }
;         }
	v_fma_f32 v47, v178, v43, v47
	v_fma_f32 v15, -v179, v43, v15
	v_fma_f32 v47, v179, v11, v47
	v_mul_f32_e32 v202, v181, v47
	v_mul_f32_e32 v203, v181, v15
	v_fma_f32 v192, v180, v15, -v202
	v_fma_f32 v193, v180, v47, v203
	v_fma_f32 v17, v184, v16, v17
	v_fma_f32 v49, v184, v48, v49
	v_fma_f32 v17, -v185, v48, v17
	v_fma_f32 v49, v185, v16, v49
	v_fma_f32 v21, v184, v20, v21
	v_fma_f32 v53, v184, v52, v53
	v_fma_f32 v21, -v185, v52, v21
	v_fma_f32 v53, v185, v20, v53
	v_fma_f32 v25, v184, v24, v25
	v_fma_f32 v57, v184, v56, v57
	v_fma_f32 v25, -v185, v56, v25
	v_fma_f32 v57, v185, v24, v57
	v_fma_f32 v29, v184, v28, v29
	v_fma_f32 v61, v184, v60, v61
	v_fma_f32 v29, -v185, v60, v29
	v_fma_f32 v61, v185, v28, v61
	v_fma_f32 v18, v184, v17, v18
	v_fma_f32 v50, v184, v49, v50
	v_fma_f32 v18, -v185, v49, v18
	v_fma_f32 v50, v185, v17, v50
	v_fma_f32 v22, v184, v21, v22
	v_fma_f32 v54, v184, v53, v54
	v_fma_f32 v22, -v185, v53, v22
	v_fma_f32 v54, v185, v21, v54
	v_fma_f32 v26, v184, v25, v26
	v_fma_f32 v58, v184, v57, v58
	v_fma_f32 v26, -v185, v57, v26
	v_fma_f32 v58, v185, v25, v58
	v_fma_f32 v30, v184, v29, v30
	v_fma_f32 v62, v184, v61, v62
	v_fma_f32 v30, -v185, v61, v30
	v_fma_f32 v62, v185, v29, v62
	v_fma_f32 v19, v184, v18, v19
	v_fma_f32 v51, v184, v50, v51
	v_fma_f32 v19, -v185, v50, v19
	v_fma_f32 v51, v185, v18, v51
	v_fma_f32 v23, v184, v22, v23
	v_fma_f32 v55, v184, v54, v55
	v_fma_f32 v23, -v185, v54, v23
	v_fma_f32 v55, v185, v22, v55
	v_fma_f32 v27, v184, v26, v27
	v_fma_f32 v59, v184, v58, v59
	v_fma_f32 v27, -v185, v58, v27
	v_fma_f32 v59, v185, v26, v59
	v_fma_f32 v31, v184, v30, v31
	v_fma_f32 v63, v184, v62, v63
	v_fma_f32 v31, -v185, v62, v31
	v_fma_f32 v63, v185, v30, v63
	v_fma_f32 v23, v186, v19, v23
	v_fma_f32 v55, v186, v51, v55
	v_fma_f32 v23, -v187, v51, v23
	v_fma_f32 v55, v187, v19, v55
	v_fma_f32 v27, v186, v23, v27
	v_fma_f32 v59, v186, v55, v59
	v_fma_f32 v27, -v187, v55, v27
	v_fma_f32 v59, v187, v23, v59
	v_fma_f32 v31, v186, v27, v31
	v_fma_f32 v63, v186, v59, v63
	v_fma_f32 v31, -v187, v59, v31
	v_fma_f32 v63, v187, v27, v63
	v_mul_f32_e32 v202, v189, v63
	v_mul_f32_e32 v203, v189, v31
	v_fma_f32 v194, v188, v31, -v202
	v_fma_f32 v195, v188, v63, v203
	s_waitcnt vmcnt(1)
	v_mfma_f32_32x32x16_bf16 v[0:15], v[152:155], v[128:131], 0
	v_mfma_f32_32x32x16_bf16 v[16:31], v[152:155], v[132:135], 0
	v_mfma_f32_32x32x16_bf16 v[32:47], v[152:155], v[136:139], 0
	v_mfma_f32_32x32x16_bf16 v[48:63], v[152:155], v[140:143], 0
	v_fma_f32 v65, v176, v64, v65
	v_fma_f32 v97, v176, v96, v97
	v_fma_f32 v65, -v177, v96, v65
	v_fma_f32 v97, v177, v64, v97
	v_fma_f32 v69, v176, v68, v69
	v_fma_f32 v101, v176, v100, v101
	v_fma_f32 v69, -v177, v100, v69
	v_fma_f32 v101, v177, v68, v101
	v_fma_f32 v73, v176, v72, v73
	v_fma_f32 v105, v176, v104, v105
	v_fma_f32 v73, -v177, v104, v73
	v_fma_f32 v105, v177, v72, v105
	v_fma_f32 v77, v176, v76, v77
	v_fma_f32 v109, v176, v108, v109
	v_fma_f32 v77, -v177, v108, v77
	v_fma_f32 v109, v177, v76, v109
	v_fma_f32 v66, v176, v65, v66
	v_fma_f32 v98, v176, v97, v98
	v_fma_f32 v66, -v177, v97, v66
	v_fma_f32 v98, v177, v65, v98
	v_fma_f32 v70, v176, v69, v70
	v_fma_f32 v102, v176, v101, v102
	v_fma_f32 v70, -v177, v101, v70
	v_fma_f32 v102, v177, v69, v102
	v_fma_f32 v74, v176, v73, v74
	v_fma_f32 v106, v176, v105, v106
	v_fma_f32 v74, -v177, v105, v74
	v_fma_f32 v106, v177, v73, v106
	v_fma_f32 v78, v176, v77, v78
	v_fma_f32 v110, v176, v109, v110
	v_fma_f32 v78, -v177, v109, v78
	v_fma_f32 v110, v177, v77, v110
	v_fma_f32 v67, v176, v66, v67
	v_fma_f32 v99, v176, v98, v99
	v_fma_f32 v67, -v177, v98, v67
	v_fma_f32 v99, v177, v66, v99
	v_fma_f32 v71, v176, v70, v71
	v_fma_f32 v103, v176, v102, v103
	v_fma_f32 v71, -v177, v102, v71
	v_fma_f32 v103, v177, v70, v103
	v_fma_f32 v75, v176, v74, v75
	v_fma_f32 v107, v176, v106, v107
	v_fma_f32 v75, -v177, v106, v75
	v_fma_f32 v107, v177, v74, v107
	v_fma_f32 v79, v176, v78, v79
	v_fma_f32 v111, v176, v110, v111
	v_fma_f32 v79, -v177, v110, v79
	v_fma_f32 v111, v177, v78, v111
	v_fma_f32 v71, v178, v67, v71
	v_fma_f32 v103, v178, v99, v103
	v_fma_f32 v71, -v179, v99, v71
	v_fma_f32 v103, v179, v67, v103
	v_fma_f32 v75, v178, v71, v75
	v_fma_f32 v107, v178, v103, v107
	v_fma_f32 v75, -v179, v103, v75
	v_fma_f32 v107, v179, v71, v107
	v_fma_f32 v79, v178, v75, v79
	v_fma_f32 v111, v178, v107, v111
	v_fma_f32 v79, -v179, v107, v79
	v_fma_f32 v111, v179, v75, v111
	v_mul_f32_e32 v202, v181, v111
	v_mul_f32_e32 v203, v181, v79
	v_fma_f32 v202, v180, v79, -v202
	v_fma_f32 v203, v180, v111, v203
	v_fma_f32 v200, v182, v192, v202
	v_fma_f32 v201, v182, v193, v203
	v_fma_f32 v200, -v183, v193, v200
	v_fma_f32 v193, v183, v192, v201
	v_mov_b32_e32 v192, v200
	v_fma_f32 v81, v184, v80, v81
	v_fma_f32 v113, v184, v112, v113
	v_fma_f32 v81, -v185, v112, v81
	v_fma_f32 v113, v185, v80, v113
	v_fma_f32 v85, v184, v84, v85
	v_fma_f32 v117, v184, v116, v117
	v_fma_f32 v85, -v185, v116, v85
	v_fma_f32 v117, v185, v84, v117
	v_fma_f32 v89, v184, v88, v89
	v_fma_f32 v121, v184, v120, v121
	v_fma_f32 v89, -v185, v120, v89
	v_fma_f32 v121, v185, v88, v121
	v_fma_f32 v93, v184, v92, v93
	v_fma_f32 v125, v184, v124, v125
	v_fma_f32 v93, -v185, v124, v93
	v_fma_f32 v125, v185, v92, v125
	v_fma_f32 v82, v184, v81, v82
	v_fma_f32 v114, v184, v113, v114
	v_fma_f32 v82, -v185, v113, v82
	v_fma_f32 v114, v185, v81, v114
	v_fma_f32 v86, v184, v85, v86
	v_fma_f32 v118, v184, v117, v118
	v_fma_f32 v86, -v185, v117, v86
	v_fma_f32 v118, v185, v85, v118
	v_fma_f32 v90, v184, v89, v90
	v_fma_f32 v122, v184, v121, v122
	v_fma_f32 v90, -v185, v121, v90
	v_fma_f32 v122, v185, v89, v122
	v_fma_f32 v94, v184, v93, v94
	v_fma_f32 v126, v184, v125, v126
	v_fma_f32 v94, -v185, v125, v94
	v_fma_f32 v126, v185, v93, v126
	v_fma_f32 v83, v184, v82, v83
	v_fma_f32 v115, v184, v114, v115
	v_fma_f32 v83, -v185, v114, v83
	v_fma_f32 v115, v185, v82, v115
	v_fma_f32 v87, v184, v86, v87
	v_fma_f32 v119, v184, v118, v119
	v_fma_f32 v87, -v185, v118, v87
	v_fma_f32 v119, v185, v86, v119
	v_fma_f32 v91, v184, v90, v91
	v_fma_f32 v123, v184, v122, v123
	v_fma_f32 v91, -v185, v122, v91
	v_fma_f32 v123, v185, v90, v123
	v_fma_f32 v95, v184, v94, v95
	v_fma_f32 v127, v184, v126, v127
	v_fma_f32 v95, -v185, v126, v95
	v_fma_f32 v127, v185, v94, v127
	v_fma_f32 v87, v186, v83, v87
	v_fma_f32 v119, v186, v115, v119
	v_fma_f32 v87, -v187, v115, v87
	v_fma_f32 v119, v187, v83, v119
	v_fma_f32 v91, v186, v87, v91
	v_fma_f32 v123, v186, v119, v123
	v_fma_f32 v91, -v187, v119, v91
	v_fma_f32 v123, v187, v87, v123
	v_fma_f32 v95, v186, v91, v95
	v_fma_f32 v127, v186, v123, v127
	v_fma_f32 v95, -v187, v123, v95
	v_fma_f32 v127, v187, v91, v127
	v_mul_f32_e32 v202, v189, v127
	v_mul_f32_e32 v203, v189, v95
	v_fma_f32 v202, v188, v95, -v202
	v_fma_f32 v203, v188, v127, v203
	v_fma_f32 v200, v190, v194, v202
	v_fma_f32 v201, v190, v195, v203
	v_fma_f32 v200, -v191, v195, v200
	v_fma_f32 v195, v191, v194, v201
	v_mov_b32_e32 v194, v200
	s_waitcnt vmcnt(0)
; __device__ __forceinline__ unsigned f2bf(float f) { unsigned u = __builtin_bit_cast(unsigned, f); return (u + 0x7fffu + ((u >> 16) & 1u)) >> 16; }
; template <bool OUT> __device__ __forceinline__ void s5_item(const PA& a, LAS unsigned char* lds, int layer, int item, int wave, int lane) {
;     ...
;         for (int t = 0; t < 16; ++t) {
;             const float br = BU[t * 132 + lane], bi = BU[t * 132 + 64 + lane];
;             const float nr = ar * xr - ai * xi + br, ni = ar * xi + ai * xr + bi; xr = nr; xi = ni;
;             if (OUT) { X[t * 136 + lane] = (bf16)f2bf(xr); X[t * 136 + 64 + lane] = (bf16)f2bf(xi); }
;         }
	v_mfma_f32_32x32x16_bf16 v[64:79], v[156:159], v[128:131], 0
	v_mfma_f32_32x32x16_bf16 v[80:95], v[156:159], v[132:135], 0
	v_mfma_f32_32x32x16_bf16 v[96:111], v[156:159], v[136:139], 0
	v_mfma_f32_32x32x16_bf16 v[112:127], v[156:159], v[140:143], 0
	s_nop 7
	s_nop 7
	v_fma_f32 v1, v176, v0, v1
	v_fma_f32 v33, v176, v32, v33
	v_fma_f32 v1, -v177, v32, v1
	v_fma_f32 v33, v177, v0, v33
	v_fma_f32 v5, v176, v4, v5
	v_fma_f32 v37, v176, v36, v37
	v_fma_f32 v5, -v177, v36, v5
	v_fma_f32 v37, v177, v4, v37
	v_fma_f32 v9, v176, v8, v9
	v_fma_f32 v41, v176, v40, v41
	v_fma_f32 v9, -v177, v40, v9
	v_fma_f32 v41, v177, v8, v41
	v_fma_f32 v13, v176, v12, v13
	v_fma_f32 v45, v176, v44, v45
	v_fma_f32 v13, -v177, v44, v13
	v_fma_f32 v45, v177, v12, v45
	v_fma_f32 v2, v176, v1, v2
	v_fma_f32 v34, v176, v33, v34
	v_fma_f32 v2, -v177, v33, v2
	v_fma_f32 v34, v177, v1, v34
	v_fma_f32 v6, v176, v5, v6
	v_fma_f32 v38, v176, v37, v38
	v_fma_f32 v6, -v177, v37, v6
	v_fma_f32 v38, v177, v5, v38
	v_fma_f32 v10, v176, v9, v10
	v_fma_f32 v42, v176, v41, v42
	v_fma_f32 v10, -v177, v41, v10
	v_fma_f32 v42, v177, v9, v42
	v_fma_f32 v14, v176, v13, v14
	v_fma_f32 v46, v176, v45, v46
	v_fma_f32 v14, -v177, v45, v14
	v_fma_f32 v46, v177, v13, v46
	v_fma_f32 v3, v176, v2, v3
	v_fma_f32 v35, v176, v34, v35
	v_fma_f32 v3, -v177, v34, v3
	v_fma_f32 v35, v177, v2, v35
	v_fma_f32 v7, v176, v6, v7
	v_fma_f32 v39, v176, v38, v39
	v_fma_f32 v7, -v177, v38, v7
	v_fma_f32 v39, v177, v6, v39
	v_fma_f32 v11, v176, v10, v11
	v_fma_f32 v43, v176, v42, v43
	v_fma_f32 v11, -v177, v42, v11
	v_fma_f32 v43, v177, v10, v43
	v_fma_f32 v15, v176, v14, v15
	v_fma_f32 v47, v176, v46, v47
	v_fma_f32 v15, -v177, v46, v15
	v_fma_f32 v47, v177, v14, v47
	v_fma_f32 v7, v178, v3, v7
	v_fma_f32 v39, v178, v35, v39
	v_fma_f32 v7, -v179, v35, v7
	v_fma_f32 v39, v179, v3, v39
	v_fma_f32 v11, v178, v7, v11
	v_fma_f32 v43, v178, v39, v43
	v_fma_f32 v11, -v179, v39, v11
	v_fma_f32 v43, v179, v7, v43
	v_fma_f32 v15, v178, v11, v15
	v_fma_f32 v47, v178, v43, v47
	v_fma_f32 v15, -v179, v43, v15
	v_fma_f32 v47, v179, v11, v47
	v_mul_f32_e32 v202, v181, v47
	v_mul_f32_e32 v203, v181, v15
	v_fma_f32 v202, v180, v15, -v202
	v_fma_f32 v203, v180, v47, v203
	v_fma_f32 v200, v182, v192, v202
	v_fma_f32 v201, v182, v193, v203
	v_fma_f32 v200, -v183, v193, v200
	v_fma_f32 v193, v183, v192, v201
	v_mov_b32_e32 v192, v200
	v_fma_f32 v17, v184, v16, v17
	v_fma_f32 v49, v184, v48, v49
	v_fma_f32 v17, -v185, v48, v17
	v_fma_f32 v49, v185, v16, v49
	v_fma_f32 v21, v184, v20, v21
	v_fma_f32 v53, v184, v52, v53
	v_fma_f32 v21, -v185, v52, v21
	v_fma_f32 v53, v185, v20, v53
	v_fma_f32 v25, v184, v24, v25
	v_fma_f32 v57, v184, v56, v57
	v_fma_f32 v25, -v185, v56, v25
	v_fma_f32 v57, v185, v24, v57
	v_fma_f32 v29, v184, v28, v29
	v_fma_f32 v61, v184, v60, v61
	v_fma_f32 v29, -v185, v60, v29
	v_fma_f32 v61, v185, v28, v61
	v_fma_f32 v18, v184, v17, v18
	v_fma_f32 v50, v184, v49, v50
	v_fma_f32 v18, -v185, v49, v18
	v_fma_f32 v50, v185, v17, v50
	v_fma_f32 v22, v184, v21, v22
	v_fma_f32 v54, v184, v53, v54
	v_fma_f32 v22, -v185, v53, v22
	v_fma_f32 v54, v185, v21, v54
	v_fma_f32 v26, v184, v25, v26
	v_fma_f32 v58, v184, v57, v58
	v_fma_f32 v26, -v185, v57, v26
	v_fma_f32 v58, v185, v25, v58
	v_fma_f32 v30, v184, v29, v30
	v_fma_f32 v62, v184, v61, v62
	v_fma_f32 v30, -v185, v61, v30
	v_fma_f32 v62, v185, v29, v62
	v_fma_f32 v19, v184, v18, v19
	v_fma_f32 v51, v184, v50, v51
	v_fma_f32 v19, -v185, v50, v19
	v_fma_f32 v51, v185, v18, v51
	v_fma_f32 v23, v184, v22, v23
	v_fma_f32 v55, v184, v54, v55
	v_fma_f32 v23, -v185, v54, v23
	v_fma_f32 v55, v185, v22, v55
	v_fma_f32 v27, v184, v26, v27
	v_fma_f32 v59, v184, v58, v59
	v_fma_f32 v27, -v185, v58, v27
	v_fma_f32 v59, v185, v26, v59
	v_fma_f32 v31, v184, v30, v31
	v_fma_f32 v63, v184, v62, v63
	v_fma_f32 v31, -v185, v62, v31
	v_fma_f32 v63, v185, v30, v63
	v_fma_f32 v23, v186, v19, v23
	v_fma_f32 v55, v186, v51, v55
	v_fma_f32 v23, -v187, v51, v23
	v_fma_f32 v55, v187, v19, v55
	v_fma_f32 v27, v186, v23, v27
	v_fma_f32 v59, v186, v55, v59
	v_fma_f32 v27, -v187, v55, v27
	v_fma_f32 v59, v187, v23, v59
	v_fma_f32 v31, v186, v27, v31
	v_fma_f32 v63, v186, v59, v63
	v_fma_f32 v31, -v187, v59, v31
	v_fma_f32 v63, v187, v27, v63
	v_mul_f32_e32 v202, v189, v63
	v_mul_f32_e32 v203, v189, v31
	v_fma_f32 v202, v188, v31, -v202
	v_fma_f32 v203, v188, v63, v203
	v_fma_f32 v200, v190, v194, v202
	v_fma_f32 v201, v190, v195, v203
	v_fma_f32 v200, -v191, v195, v200
	v_fma_f32 v195, v191, v194, v201
	v_mov_b32_e32 v194, v200
	v_fma_f32 v65, v176, v64, v65
	v_fma_f32 v97, v176, v96, v97
	v_fma_f32 v65, -v177, v96, v65
	v_fma_f32 v97, v177, v64, v97
	v_fma_f32 v69, v176, v68, v69
	v_fma_f32 v101, v176, v100, v101
	v_fma_f32 v69, -v177, v100, v69
	v_fma_f32 v101, v177, v68, v101
	v_fma_f32 v73, v176, v72, v73
	v_fma_f32 v105, v176, v104, v105
	v_fma_f32 v73, -v177, v104, v73
; __device__ __forceinline__ unsigned f2bf(float f) { unsigned u = __builtin_bit_cast(unsigned, f); return (u + 0x7fffu + ((u >> 16) & 1u)) >> 16; }
; template <bool OUT> __device__ __forceinline__ void s5_item(const PA& a, LAS unsigned char* lds, int layer, int item, int wave, int lane) {
;     ...
;             const float nr = ar * xr - ai * xi + br, ni = ar * xi + ai * xr + bi; xr = nr; xi = ni;
;             if (OUT) { X[t * 136 + lane] = (bf16)f2bf(xr); X[t * 136 + 64 + lane] = (bf16)f2bf(xi); }
;         }
;     ...
;     if (!OUT) { XL[c * 128 + lane] = xr; XL[c * 128 + 64 + lane] = xi; }
	v_fma_f32 v105, v177, v72, v105
	v_fma_f32 v77, v176, v76, v77
	v_fma_f32 v109, v176, v108, v109
	v_fma_f32 v77, -v177, v108, v77
	v_fma_f32 v109, v177, v76, v109
	v_fma_f32 v66, v176, v65, v66
	v_fma_f32 v98, v176, v97, v98
	v_fma_f32 v66, -v177, v97, v66
	v_fma_f32 v98, v177, v65, v98
	v_fma_f32 v70, v176, v69, v70
	v_fma_f32 v102, v176, v101, v102
	v_fma_f32 v70, -v177, v101, v70
	v_fma_f32 v102, v177, v69, v102
	v_fma_f32 v74, v176, v73, v74
	v_fma_f32 v106, v176, v105, v106
	v_fma_f32 v74, -v177, v105, v74
	v_fma_f32 v106, v177, v73, v106
	v_fma_f32 v78, v176, v77, v78
	v_fma_f32 v110, v176, v109, v110
	v_fma_f32 v78, -v177, v109, v78
	v_fma_f32 v110, v177, v77, v110
	v_fma_f32 v67, v176, v66, v67
	v_fma_f32 v99, v176, v98, v99
	v_fma_f32 v67, -v177, v98, v67
	v_fma_f32 v99, v177, v66, v99
	v_fma_f32 v71, v176, v70, v71
	v_fma_f32 v103, v176, v102, v103
	v_fma_f32 v71, -v177, v102, v71
	v_fma_f32 v103, v177, v70, v103
	v_fma_f32 v75, v176, v74, v75
	v_fma_f32 v107, v176, v106, v107
	v_fma_f32 v75, -v177, v106, v75
	v_fma_f32 v107, v177, v74, v107
	v_fma_f32 v79, v176, v78, v79
	v_fma_f32 v111, v176, v110, v111
	v_fma_f32 v79, -v177, v110, v79
	v_fma_f32 v111, v177, v78, v111
	v_fma_f32 v71, v178, v67, v71
	v_fma_f32 v103, v178, v99, v103
	v_fma_f32 v71, -v179, v99, v71
	v_fma_f32 v103, v179, v67, v103
	v_fma_f32 v75, v178, v71, v75
	v_fma_f32 v107, v178, v103, v107
	v_fma_f32 v75, -v179, v103, v75
	v_fma_f32 v107, v179, v71, v107
	v_fma_f32 v79, v178, v75, v79
	v_fma_f32 v111, v178, v107, v111
	v_fma_f32 v79, -v179, v107, v79
	v_fma_f32 v111, v179, v75, v111
	v_mul_f32_e32 v202, v181, v111
	v_mul_f32_e32 v203, v181, v79
	v_fma_f32 v202, v180, v79, -v202
	v_fma_f32 v203, v180, v111, v203
	v_fma_f32 v200, v182, v192, v202
	v_fma_f32 v201, v182, v193, v203
	v_fma_f32 v200, -v183, v193, v200
	v_fma_f32 v193, v183, v192, v201
	v_mov_b32_e32 v192, v200
	v_fma_f32 v81, v184, v80, v81
	v_fma_f32 v113, v184, v112, v113
	v_fma_f32 v81, -v185, v112, v81
	v_fma_f32 v113, v185, v80, v113
	v_fma_f32 v85, v184, v84, v85
	v_fma_f32 v117, v184, v116, v117
	v_fma_f32 v85, -v185, v116, v85
	v_fma_f32 v117, v185, v84, v117
	v_fma_f32 v89, v184, v88, v89
	v_fma_f32 v121, v184, v120, v121
	v_fma_f32 v89, -v185, v120, v89
	v_fma_f32 v121, v185, v88, v121
	v_fma_f32 v93, v184, v92, v93
	v_fma_f32 v125, v184, v124, v125
	v_fma_f32 v93, -v185, v124, v93
	v_fma_f32 v125, v185, v92, v125
	v_fma_f32 v82, v184, v81, v82
	v_fma_f32 v114, v184, v113, v114
	v_fma_f32 v82, -v185, v113, v82
	v_fma_f32 v114, v185, v81, v114
	v_fma_f32 v86, v184, v85, v86
	v_fma_f32 v118, v184, v117, v118
	v_fma_f32 v86, -v185, v117, v86
	v_fma_f32 v118, v185, v85, v118
	v_fma_f32 v90, v184, v89, v90
	v_fma_f32 v122, v184, v121, v122
	v_fma_f32 v90, -v185, v121, v90
	v_fma_f32 v122, v185, v89, v122
	v_fma_f32 v94, v184, v93, v94
	v_fma_f32 v126, v184, v125, v126
	v_fma_f32 v94, -v185, v125, v94
	v_fma_f32 v126, v185, v93, v126
	v_fma_f32 v83, v184, v82, v83
	v_fma_f32 v115, v184, v114, v115
	v_fma_f32 v83, -v185, v114, v83
	v_fma_f32 v115, v185, v82, v115
	v_fma_f32 v87, v184, v86, v87
	v_fma_f32 v119, v184, v118, v119
	v_fma_f32 v87, -v185, v118, v87
	v_fma_f32 v119, v185, v86, v119
	v_fma_f32 v91, v184, v90, v91
	v_fma_f32 v123, v184, v122, v123
	v_fma_f32 v91, -v185, v122, v91
	v_fma_f32 v123, v185, v90, v123
	v_fma_f32 v95, v184, v94, v95
	v_fma_f32 v127, v184, v126, v127
	v_fma_f32 v95, -v185, v126, v95
	v_fma_f32 v127, v185, v94, v127
	v_fma_f32 v87, v186, v83, v87
	v_fma_f32 v119, v186, v115, v119
	v_fma_f32 v87, -v187, v115, v87
	v_fma_f32 v119, v187, v83, v119
	v_fma_f32 v91, v186, v87, v91
	v_fma_f32 v123, v186, v119, v123
	v_fma_f32 v91, -v187, v119, v91
	v_fma_f32 v123, v187, v87, v123
	v_fma_f32 v95, v186, v91, v95
	v_fma_f32 v127, v186, v123, v127
	v_fma_f32 v95, -v187, v123, v95
	v_fma_f32 v127, v187, v91, v127
	v_mul_f32_e32 v202, v189, v127
	v_mul_f32_e32 v203, v189, v95
	v_fma_f32 v202, v188, v95, -v202
	v_fma_f32 v203, v188, v127, v203
	v_fma_f32 v200, v190, v194, v202
	v_fma_f32 v201, v190, v195, v203
	v_fma_f32 v200, -v191, v195, v200
	v_fma_f32 v195, v191, v194, v201
	v_mov_b32_e32 v194, v200
	v_mov_b32_e32 v196, v192
	v_mov_b32_e32 v197, v193
	v_mov_b32_e32 v198, v194
	v_mov_b32_e32 v199, v195
	s_nop 1
	v_permlane32_swap_b32_e32 v192, v196
	v_permlane32_swap_b32_e32 v193, v197
	v_permlane32_swap_b32_e32 v194, v198
	v_permlane32_swap_b32_e32 v195, v199
	v_add_f32_e32 v192, v192, v196
	v_add_f32_e32 v193, v193, v197
	v_add_f32_e32 v194, v194, v198
	v_add_f32_e32 v195, v195, v199
	s_lshl_b32 s2, s8, 9
	s_add_u32 s2, s2, s68
	s_addc_u32 s3, s69, 0
	s_add_u32 s2, s2, 0x1f00000
	s_addc_u32 s3, s3, 0
	s_mov_b32 exec_hi, 0
	global_store_dword v204, v192, s[2:3]
	global_store_dword v204, v194, s[2:3] offset:128
	global_store_dword v204, v193, s[2:3] offset:256
	global_store_dword v204, v195, s[2:3] offset:384
	s_mov_b64 exec, -1
